# attention tail: last K/V tile written to LDS just before the mid-tail barrier (load latency hidden behind the previous tile's compute)
# speedup vs baseline: 1.0036x; 1.0036x over previous
; DI void attn_item(const P& p, int l, int item, char* smem) {
;     ...
;   for (int kt = -1; kt < 128; ++kt) {
;     if (kt + 1 < 128) {
;       u16* Kd = Ks + ((kt + 1) & 1) * (256 * 72);
;       u16* Vd = Kd + 2 * 64 * 72;
; #pragma unroll
;       for (int i = 0; i < 2; ++i) {
;         const int row = tid >> 3, kc = tid & 7;
;         *(u32x4*)(Kd + (i * 64 + row) * 72 + kc * 8) = kreg[i];
;       }
; #pragma unroll
;       for (int i = 0; i < 2; ++i) {
;         const int cid = tid + NT * i;
;         const int e = cid >> 3, kc = cid & 7;
;         uint2 w0; w0.x = vreg[i][0]; w0.y = vreg[i][1];
;         uint2 w1; w1.x = vreg[i][2]; w1.y = vreg[i][3];
;         u16* vd = Vd + e * 72 + (kc >> 1) * 16 + (kc & 1) * 4;
;         *(uint2*)vd = w0;
;         *(uint2*)(vd + 8) = w1;
;       }
;     }
;     if (kt + 2 < 128) {
;       const int kn = kt + 2;
; #pragma unroll
;       for (int i = 0; i < 2; ++i) kreg[i] = *(const u32x4*)(kbase + ((size_t)i * SEQ + kn * 64) * 64 + tid * 8);
; #pragma unroll
;       for (int i = 0; i < 2; ++i) {
;         const int cid = tid + NT * i;
;         const int e = cid >> 3, kc = cid & 7;
;         vreg[i] = *(const u32x4*)(vbase + (size_t)e * VTP + kn * 64 + kc * 8);
;       }
;     }
;     __builtin_amdgcn_sched_barrier(0x38F);
;     if (kt >= 0) {
;       const u16* Kc = Ks + (kt & 1) * (256 * 72);
;       const u16* Vc = Kc + 2 * 64 * 72;
;       bf16x8 kf[8];
; #pragma unroll
;       for (int i = 0; i < 8; ++i)
;         kf[i] = *(const bf16x8*)(Kc + (c * 64 + 32 * (i & 1) + li) * 72 + 16 * (i >> 1) + 8 * g);
;       u32x4 vf[16];
; #pragma unroll
;       for (int i = 0; i < 16; ++i) {
;         const int eb = i & 3, s = (i >> 2) & 1, kb = i >> 3;
;         vf[i] = *(const u32x4*)(Vc + (32 * eb + li) * 72 + 32 * kb + 16 * s + 8 * g);
;       }
;       f32x16 S[2];
; #pragma unroll
;       for (int kb = 0; kb < 2; ++kb)
; #pragma unroll
;         for (int r = 0; r < 16; ++r) S[kb][r] = negm;
; #pragma unroll
;       for (int i = 0; i < 8; ++i) S[i & 1] = MFMA(kf[i], qf[i >> 1], S[i & 1]);
;       u32x4 pk[4];
;       float sum = 0.f;
; #pragma unroll
;       for (int ch = 0; ch < 4; ++ch) {
;         const int kb = ch >> 1, s = ch & 1;
; #pragma unroll
;         for (int j2 = 0; j2 < 4; ++j2) {
;           const float p0 = __builtin_amdgcn_exp2f(S[kb][8 * s + 2 * j2]);
.Lat_exit:
	global_load_dwordx4 v[232:235], v[148:149], off
	global_load_dwordx4 v[228:231], v[156:157], off
	global_load_dwordx4 v[236:239], v[146:147], off
	global_load_dwordx4 v[240:243], v[144:145], off
	v_add_f32_e64 v167, v167, v190
	v_add_f32_e64 v191, v191, v196
	s_nop 0
	v_add_f32_e64 v167, v167, v191
	v_mov_b32_e32 v176, v168
	v_add_u32_e32 v177, 0xd800, v169
	v_add_u32_e32 v178, 0xd800, v143
	v_add3_u32 v129, 0, v175, v188
	ds_read_b128 v[80:83], v129
	ds_read_b128 v[130:133], v129 offset:4608
	v_add3_u32 v128, 0, v174, v188
	ds_read_b128 v[134:137], v128 offset:18432
	v_readlane_b32 s6, v248, 5
	s_waitcnt lgkmcnt(2)
	v_mfma_f32_32x32x16_bf16 v[96:111], v[80:83], v[112:115], v[16:31]
	s_waitcnt lgkmcnt(1)
	v_mfma_f32_32x32x16_bf16 v[80:95], v[130:133], v[112:115], v[16:31]
	ds_read_b128 v[130:133], v129 offset:32
	s_waitcnt lgkmcnt(0)
	v_mfma_f32_32x32x16_bf16 v[96:111], v[130:133], v[116:119], v[96:111]
	ds_read_b128 v[130:133], v129 offset:4640
	s_waitcnt lgkmcnt(0)
	v_mfma_f32_32x32x16_bf16 v[80:95], v[130:133], v[116:119], v[80:95]
	ds_read_b128 v[130:133], v129 offset:64
	s_waitcnt lgkmcnt(0)
	v_mfma_f32_32x32x16_bf16 v[96:111], v[130:133], v[124:127], v[96:111]
	ds_read_b128 v[130:133], v129 offset:4672
	s_waitcnt lgkmcnt(0)
	v_mfma_f32_32x32x16_bf16 v[80:95], v[130:133], v[124:127], v[80:95]
	ds_read_b128 v[130:133], v129 offset:96
	s_waitcnt lgkmcnt(0)
	v_mfma_f32_32x32x16_bf16 v[96:111], v[130:133], v[120:123], v[96:111]
	ds_read_b128 v[130:133], v129 offset:4704
	s_nop 10
	v_exp_f32_e32 v144, v100
	v_exp_f32_e32 v145, v101
	v_exp_f32_e32 v146, v102
	v_exp_f32_e32 v147, v103
	ds_read_b128 v[100:103], v128 offset:23040
	v_exp_f32_e32 v138, v96
	v_exp_f32_e32 v139, v97
	v_exp_f32_e32 v142, v98
	v_exp_f32_e32 v143, v99
	v_cvt_pk_bf16_f32 v98, v144, v145
	v_cvt_pk_bf16_f32 v96, v138, v139
	v_cvt_pk_bf16_f32 v99, v146, v147
	v_cvt_pk_bf16_f32 v97, v142, v143
	v_exp_f32_e32 v108, v108
	v_exp_f32_e32 v109, v109
	s_waitcnt lgkmcnt(0)
	v_mfma_f32_32x32x16_bf16 v[48:63], v[100:103], v[96:99], v[48:63]
	ds_read_b128 v[100:103], v128 offset:27648
	v_exp_f32_e32 v110, v110
	v_exp_f32_e32 v111, v111
	v_mfma_f32_32x32x16_bf16 v[80:95], v[130:133], v[120:123], v[80:95]
	s_waitcnt lgkmcnt(0)
	v_mfma_f32_32x32x16_bf16 v[32:47], v[100:103], v[96:99], v[32:47]
	ds_read_b128 v[100:103], v128 offset:32256
	ds_read_b128 v[130:133], v128 offset:18464
	s_nop 7
	v_exp_f32_e32 v148, v84
	v_exp_f32_e32 v149, v85
	v_exp_f32_e32 v150, v86
	v_exp_f32_e32 v151, v87
	v_exp_f32_e32 v152, v88
	v_exp_f32_e32 v153, v89
	s_waitcnt lgkmcnt(1)
	v_mfma_f32_32x32x16_bf16 v[0:15], v[100:103], v[96:99], v[0:15]
	ds_read_b128 v[100:103], v128 offset:23072
	v_exp_f32_e32 v154, v90
	v_exp_f32_e32 v155, v91
	v_exp_f32_e32 v156, v92
	v_exp_f32_e32 v157, v93
	v_exp_f32_e32 v168, v94
	v_exp_f32_e32 v169, v95
	v_mfma_f32_32x32x16_bf16 v[64:79], v[134:137], v[96:99], v[64:79]
	v_exp_f32_e32 v134, v104
	v_exp_f32_e32 v135, v105
	v_exp_f32_e32 v136, v106
	v_exp_f32_e32 v137, v107
	v_cvt_pk_bf16_f32 v98, v108, v109
	v_cvt_pk_bf16_f32 v96, v134, v135
	v_cvt_pk_bf16_f32 v99, v110, v111
	v_cvt_pk_bf16_f32 v97, v136, v137
	v_add_f32_e32 v88, v165, v166
	v_mul_f32_e32 v165, 0x3fb8aa3b, v88
	s_waitcnt lgkmcnt(0)
	v_mfma_f32_32x32x16_bf16 v[48:63], v[100:103], v[96:99], v[48:63]
	ds_read_b128 v[100:103], v128 offset:27680
	v_add_f32_e32 v134, v134, v135
	s_waitcnt lgkmcnt(0)
	v_mfma_f32_32x32x16_bf16 v[32:47], v[100:103], v[96:99], v[32:47]
	ds_read_b128 v[100:103], v128 offset:32288
	ds_read_b128 v[104:107], v128 offset:18496
	ds_read_b128 v[84:87], v128 offset:23104
	v_mfma_f32_32x32x16_bf16 v[64:79], v[130:133], v[96:99], v[64:79]
	v_exp_f32_e32 v130, v80
	v_exp_f32_e32 v131, v81
	v_exp_f32_e32 v132, v82
	v_exp_f32_e32 v133, v83
	v_cvt_pk_bf16_f32 v82, v148, v149
	v_cvt_pk_bf16_f32 v80, v130, v131
	v_cvt_pk_bf16_f32 v83, v150, v151
	v_cvt_pk_bf16_f32 v81, v132, v133
	s_waitcnt lgkmcnt(2)
	v_mfma_f32_32x32x16_bf16 v[0:15], v[100:103], v[96:99], v[0:15]
	s_waitcnt lgkmcnt(0)
	v_mfma_f32_32x32x16_bf16 v[48:63], v[84:87], v[80:83], v[48:63]
	ds_read_b128 v[84:87], v128 offset:27712
	s_waitcnt lgkmcnt(0)
	v_mfma_f32_32x32x16_bf16 v[32:47], v[84:87], v[80:83], v[32:47]
	ds_read_b128 v[84:87], v128 offset:32320
	ds_read_b128 v[96:99], v128 offset:18528
	s_waitcnt lgkmcnt(1)
	v_mfma_f32_32x32x16_bf16 v[0:15], v[84:87], v[80:83], v[0:15]
	ds_read_b128 v[84:87], v128 offset:23136
	v_mfma_f32_32x32x16_bf16 v[64:79], v[104:107], v[80:83], v[64:79]
	v_cvt_pk_bf16_f32 v80, v152, v153
	v_cvt_pk_bf16_f32 v81, v154, v155
	v_cvt_pk_bf16_f32 v82, v156, v157
	v_cvt_pk_bf16_f32 v83, v168, v169
	s_waitcnt lgkmcnt(0)
	s_nop 0
	v_mfma_f32_32x32x16_bf16 v[48:63], v[84:87], v[80:83], v[48:63]
	ds_read_b128 v[84:87], v128 offset:27744
	s_waitcnt lgkmcnt(0)
	v_mfma_f32_32x32x16_bf16 v[32:47], v[84:87], v[80:83], v[32:47]
	s_waitcnt vmcnt(0)
	ds_write_b128 v176, v[228:231] offset:36864
	ds_write_b128 v176, v[232:235] offset:46080
	ds_write2_b64 v177, v[236:237], v[238:239] offset1:2
	ds_write2_b64 v178, v[240:241], v[242:243] offset1:2
	ds_read_b128 v[84:87], v128 offset:32352
	s_waitcnt lgkmcnt(0)
	s_barrier
; #define MFMA(a, b, c) __builtin_amdgcn_mfma_f32_32x32x16_bf16((a), (b), (c), 0, 0, 0)
; DI void attn_item(const P& p, int l, int item, char* smem) {
;     ...
;     if (kt >= 0) {
;       const u16* Kc = Ks + (kt & 1) * (256 * 72);
;       const u16* Vc = Kc + 2 * 64 * 72;
;       bf16x8 kf[8];
; #pragma unroll
;       for (int i = 0; i < 8; ++i)
;         kf[i] = *(const bf16x8*)(Kc + (c * 64 + 32 * (i & 1) + li) * 72 + 16 * (i >> 1) + 8 * g);
;       u32x4 vf[16];
; #pragma unroll
;       for (int i = 0; i < 16; ++i) {
;         const int eb = i & 3, s = (i >> 2) & 1, kb = i >> 3;
;         vf[i] = *(const u32x4*)(Vc + (32 * eb + li) * 72 + 32 * kb + 16 * s + 8 * g);
;       }
;       f32x16 S[2];
; #pragma unroll
;       for (int kb = 0; kb < 2; ++kb)
; #pragma unroll
;         for (int r = 0; r < 16; ++r) S[kb][r] = negm;
; #pragma unroll
;       for (int i = 0; i < 8; ++i) S[i & 1] = MFMA(kf[i], qf[i >> 1], S[i & 1]);
;       u32x4 pk[4];
;       float sum = 0.f;
; #pragma unroll
;       for (int ch = 0; ch < 4; ++ch) {
;         const int kb = ch >> 1, s = ch & 1;
; #pragma unroll
;         for (int j2 = 0; j2 < 4; ++j2) {
;           const float p0 = __builtin_amdgcn_exp2f(S[kb][8 * s + 2 * j2]);
;           const float p1 = __builtin_amdgcn_exp2f(S[kb][8 * s + 2 * j2 + 1]);
;           sum += p0 + p1;
;           pk[ch][j2] = pack2(p0, p1);
;         }
;       }
;       ls += sum;
; #pragma unroll
;       for (int i = 0; i < 16; ++i) {
;         const int eb = i & 3, ch = i >> 2;
;         O[eb] = MFMA(__builtin_bit_cast(bf16x8, vf[i]), __builtin_bit_cast(bf16x8, pk[ch]), O[eb]);
;       }
;     }
	v_mfma_f32_32x32x16_bf16 v[64:79], v[96:99], v[80:83], v[64:79]
	ds_read_b128 v[96:99], v129 offset:36864
	ds_read_b128 v[100:103], v129 offset:41472
	ds_read_b128 v[104:107], v129 offset:36896
	v_mfma_f32_32x32x16_bf16 v[0:15], v[84:87], v[80:83], v[0:15]
	v_add_f32_e32 v80, v138, v139
	v_add_f32_e32 v80, 0, v80
	v_add_f32_e32 v81, v142, v143
	v_add_f32_e32 v138, v81, v80
	v_exp_f32_e32 v139, v165
	s_waitcnt lgkmcnt(2)
	v_mfma_f32_32x32x16_bf16 v[80:95], v[96:99], v[112:115], v[16:31]
	v_add_f32_e32 v96, v144, v145
	v_add_f32_e32 v96, v96, v138
	v_add_f32_e32 v97, v146, v147
	v_add_f32_e32 v138, v97, v96
	v_add_f32_e32 v134, v134, v138
	ds_read_b128 v[96:99], v129 offset:41504
	s_waitcnt lgkmcnt(2)
	v_mfma_f32_32x32x16_bf16 v[16:31], v[100:103], v[112:115], v[16:31]
	v_add_f32_e32 v100, v136, v137
	v_add_f32_e32 v100, v100, v134
	v_add_f32_e32 v101, v108, v109
	v_add_f32_e32 v100, v101, v100
	v_add_f32_e32 v101, v110, v111
	v_add_f32_e32 v100, v101, v100
	v_add_f32_e32 v101, v130, v131
	v_add_f32_e32 v100, v101, v100
	v_add_f32_e32 v101, v132, v133
	s_waitcnt lgkmcnt(1)
	v_mfma_f32_32x32x16_bf16 v[80:95], v[104:107], v[116:119], v[80:95]
	v_add_f32_e32 v104, v101, v100
	ds_read_b128 v[100:103], v129 offset:36928
	v_add_f32_e32 v105, v148, v149
	v_add_f32_e32 v104, v105, v104
	v_add_f32_e32 v105, v150, v151
	v_add_f32_e32 v108, v105, v104
	v_add_f32_e32 v109, v152, v153
	s_waitcnt lgkmcnt(0)
	v_mfma_f32_32x32x16_bf16 v[80:95], v[100:103], v[124:127], v[80:95]
	v_add_f32_e32 v110, v154, v155
	v_add_f32_e32 v100, v109, v108
	v_add_f32_e32 v111, v156, v157
	v_add_f32_e32 v100, v110, v100
	v_add_f32_e32 v112, v168, v169
	v_add_f32_e32 v100, v111, v100
	v_add_f32_e32 v108, v112, v100
	v_mfma_f32_32x32x16_bf16 v[16:31], v[96:99], v[116:119], v[16:31]
	ds_read_b128 v[96:99], v129 offset:41536
	ds_read_b128 v[104:107], v129 offset:36960
	ds_read_b128 v[100:103], v129 offset:41568
	v_add_f32_e32 v129, v167, v108
	v_add_f32_e32 v108, v163, v164
	v_mul_f32_e32 v138, 0x3fb8aa3b, v108
	v_add_u32_e32 v150, 0xd800, v128
	s_waitcnt lgkmcnt(1)
	v_mfma_f32_32x32x16_bf16 v[80:95], v[104:107], v[120:123], v[80:95]
	v_mfma_f32_32x32x16_bf16 v[16:31], v[96:99], v[124:127], v[16:31]
	s_nop 10
	v_exp_f32_e32 v154, v80
	v_exp_f32_e32 v155, v81
	v_exp_f32_e32 v156, v82
	v_exp_f32_e32 v157, v83
	v_exp_f32_e32 v163, v84
	v_exp_f32_e32 v164, v85
	v_exp_f32_e32 v165, v86
	v_exp_f32_e32 v166, v87
	ds_read_b128 v[96:99], v128 offset:55296
	ds_read_b128 v[108:111], v128 offset:55328
	ds_read_b128 v[112:115], v128 offset:59904
	ds_read_b128 v[116:119], v128 offset:59936
	s_waitcnt lgkmcnt(4)
	v_mfma_f32_32x32x16_bf16 v[16:31], v[100:103], v[120:123], v[16:31]
	ds_read_b128 v[84:87], v128 offset:64512
	ds_read_b128 v[100:103], v128 offset:64544
	v_cvt_pk_bf16_f32 v80, v154, v155
	v_cvt_pk_bf16_f32 v81, v156, v157
	v_cvt_pk_bf16_f32 v82, v163, v164
	v_cvt_pk_bf16_f32 v83, v165, v166
	s_nop 5
	v_exp_f32_e32 v16, v16
	s_waitcnt lgkmcnt(5)
	v_mfma_f32_32x32x16_bf16 v[64:79], v[96:99], v[80:83], v[64:79]
	ds_read_b128 v[96:99], v150 offset:13824
	ds_read_b128 v[104:107], v150 offset:13856
	ds_read_b128 v[120:123], v128 offset:55360
	ds_read_b128 v[124:127], v128 offset:55392
	ds_read_b128 v[130:133], v128 offset:59968
	ds_read_b128 v[134:137], v128 offset:60000
	ds_read_b128 v[142:145], v128 offset:64576
	v_exp_f32_e32 v17, v17
	v_exp_f32_e32 v18, v18
	v_exp_f32_e32 v19, v19
	v_exp_f32_e32 v20, v20
	v_exp_f32_e32 v21, v21
	v_exp_f32_e32 v22, v22
	s_waitcnt lgkmcnt(10)
	v_mfma_f32_32x32x16_bf16 v[48:63], v[112:115], v[80:83], v[48:63]
	ds_read_b128 v[112:115], v128 offset:64608
	ds_read_b128 v[146:149], v150 offset:13888
	ds_read_b128 v[150:153], v150 offset:13920
	v_add_f32_e32 v128, v154, v155
	v_add_f32_e32 v128, 0, v128
	v_add_f32_e32 v154, v156, v157
	v_add_f32_e32 v128, v154, v128
	v_exp_f32_e32 v23, v23
	s_waitcnt lgkmcnt(0)
	v_mfma_f32_32x32x16_bf16 v[32:47], v[84:87], v[80:83], v[32:47]
	v_exp_f32_e32 v85, v88
	v_exp_f32_e32 v86, v89
	v_exp_f32_e32 v87, v90
	v_exp_f32_e32 v88, v91
	v_add_f32_e32 v84, v163, v164
	v_exp_f32_e32 v89, v92
	v_exp_f32_e32 v90, v93
	v_add_f32_e32 v84, v84, v128
	v_mfma_f32_32x32x16_bf16 v[0:15], v[96:99], v[80:83], v[0:15]
	v_exp_f32_e32 v91, v94
	v_exp_f32_e32 v92, v95
	v_add_f32_e32 v93, v165, v166
	v_cvt_pk_bf16_f32 v80, v85, v86
	v_add_f32_e32 v84, v93, v84
	v_add_f32_e32 v85, v85, v86
	v_add_f32_e32 v84, v85, v84
	v_add_f32_e32 v85, v87, v88
	v_add_f32_e32 v84, v85, v84
	v_add_f32_e32 v85, v89, v90
	v_add_f32_e32 v84, v85, v84
	v_add_f32_e32 v85, v91, v92
	v_add_f32_e32 v84, v85, v84
	v_add_f32_e32 v85, v16, v17
	v_add_f32_e32 v84, v85, v84
	v_cvt_pk_bf16_f32 v16, v16, v17
	v_add_f32_e32 v17, v18, v19
	v_cvt_pk_bf16_f32 v81, v87, v88
	v_cvt_pk_bf16_f32 v82, v89, v90
	v_cvt_pk_bf16_f32 v83, v91, v92
	v_add_f32_e32 v84, v17, v84
	v_cvt_pk_bf16_f32 v17, v18, v19
	v_add_f32_e32 v18, v20, v21
	v_mfma_f32_32x32x16_bf16 v[64:79], v[108:111], v[80:83], v[64:79]
	v_cvt_pk_bf16_f32 v19, v22, v23
	s_barrier
; #define MFMA(a, b, c) __builtin_amdgcn_mfma_f32_32x32x16_bf16((a), (b), (c), 0, 0, 0)
; DI void attn_item(const P& p, int l, int item, char* smem) {
;     ...
;       for (int i = 0; i < 16; ++i) {
;         const int eb = i & 3, ch = i >> 2;
;         O[eb] = MFMA(__builtin_bit_cast(bf16x8, vf[i]), __builtin_bit_cast(bf16x8, pk[ch]), O[eb]);
;       }
;     }
;     __syncthreads();
;   }
;   const float lt = ls + __shfl_xor(ls, 32);
;   const float inv = (c == 0) ? (1.0f / lt) : (lam / lt);
;   float* exch = (float*)smem + qg * (64 * 64);
;   if (c == 1) {
; #pragma unroll
;     for (int eb = 0; eb < 4; ++eb)
; #pragma unroll
;       for (int r = 0; r < 16; ++r) exch[(eb * 16 + r) * 64 + lane] = O[eb][r] * inv;
;   }
;   __syncthreads();
;   if (c == 0) {
;     float ss = 0.f;
; #pragma unroll
;     for (int eb = 0; eb < 4; ++eb)
; #pragma unroll
;       for (int r = 0; r < 16; ++r) {
;         const float o = O[eb][r] * inv - exch[(eb * 16 + r) * 64 + lane];
;         O[eb][r] = o;
;         ss += o * o;
;       }
;     ss += __shfl_xor(ss, 32);
;     const float rn = rsqrtf(ss * (1.0f / 128.0f) + 1e-5f) * (1.0f - lam_init);
;     const size_t tok = (size_t)b * SEQ + tq;
; #pragma unroll
;     for (int eb = 0; eb < 4; ++eb)
; #pragma unroll
;       for (int rq = 0; rq < 4; ++rq) {
;         const int e = 32 * eb + 8 * rq + 4 * g;
;         const uint2 gt = *(const uint2*)(p.AG + tok * 512 + h * 128 + e);
;         const float4 sg = *(const float4*)(p.subg + l * 128 + e);
	v_mfma_f32_32x32x16_bf16 v[48:63], v[116:119], v[80:83], v[48:63]
	v_mfma_f32_32x32x16_bf16 v[32:47], v[100:103], v[80:83], v[32:47]
	v_mfma_f32_32x32x16_bf16 v[0:15], v[104:107], v[80:83], v[0:15]
	v_add_f32_e32 v80, v18, v84
	v_cvt_pk_bf16_f32 v18, v20, v21
	v_add_f32_e32 v20, v22, v23
	v_exp_f32_e32 v21, v24
	v_exp_f32_e32 v22, v25
	v_exp_f32_e32 v23, v26
	v_exp_f32_e32 v25, v27
	v_add_f32_e32 v24, v20, v80
	v_add_f32_e32 v26, v21, v22
	v_cvt_pk_bf16_f32 v20, v21, v22
	v_add_f32_e32 v27, v23, v25
	v_cvt_pk_bf16_f32 v21, v23, v25
	v_exp_f32_e32 v22, v28
	v_exp_f32_e32 v23, v29
	v_exp_f32_e32 v25, v30
	v_exp_f32_e32 v28, v31
	v_add_f32_e32 v24, v26, v24
	v_add_f32_e32 v29, v22, v23
	v_add_f32_e32 v24, v27, v24
	v_add_f32_e32 v30, v25, v28
	v_add_f32_e32 v24, v29, v24
	v_mfma_f32_32x32x16_bf16 v[64:79], v[120:123], v[16:19], v[64:79]
	v_cvt_pk_bf16_f32 v22, v22, v23
	v_cvt_pk_bf16_f32 v23, v25, v28
	v_mfma_f32_32x32x16_bf16 v[48:63], v[130:133], v[16:19], v[48:63]
	v_mfma_f32_32x32x16_bf16 v[32:47], v[142:145], v[16:19], v[32:47]
	v_mfma_f32_32x32x16_bf16 v[0:15], v[146:149], v[16:19], v[0:15]
	v_add_f32_e32 v16, v30, v24
	v_exp_f32_e32 v17, v138
	v_add_f32_e32 v16, v129, v16
	ds_bpermute_b32 v18, v158, v16
	v_sub_f32_e32 v17, v17, v139
	v_add_f32_e32 v17, s6, v17
	s_movk_i32 s6, 0x100
	v_cmp_gt_u32_e64 s[6:7], s6, v161
	s_waitcnt lgkmcnt(0)
	v_add_f32_e32 v16, v16, v18
	v_mfma_f32_32x32x16_bf16 v[64:79], v[124:127], v[20:23], v[64:79]
	v_cndmask_b32_e64 v17, v17, 1.0, s[6:7]
	v_div_scale_f32 v18, s[10:11], v16, v16, v17
	v_rcp_f32_e32 v19, v18
	s_nop 0
	v_fma_f32 v24, -v18, v19, 1.0
	v_mfma_f32_32x32x16_bf16 v[48:63], v[134:137], v[20:23], v[48:63]
	v_fmac_f32_e32 v19, v24, v19
	v_div_scale_f32 v24, vcc, v17, v16, v17
	v_mul_f32_e32 v25, v24, v19
	v_fma_f32 v26, -v18, v25, v24
	v_fmac_f32_e32 v25, v26, v19
	v_fma_f32 v18, -v18, v25, v24
	v_mfma_f32_32x32x16_bf16 v[32:47], v[112:115], v[20:23], v[32:47]
	v_div_fmas_f32 v18, v18, v19, v25
	v_div_fixup_f32 v80, v18, v16, v17
	v_lshl_add_u32 v16, v162, 14, 0
	v_cmp_eq_u32_e32 vcc, 1, v160
	v_lshl_add_u32 v18, v141, 2, v16
	v_mfma_f32_32x32x16_bf16 v[0:15], v[150:153], v[20:23], v[0:15]
	s_and_saveexec_b64 s[10:11], s[6:7]
	s_cbranch_execz .Lfin_nl
	v_and_b32_e32 v142, 15, v161
	v_bfe_u32 v143, v161, 4, 2
	v_and_b32_e32 v144, 0xffffffe0, v140
	v_add_u32_e32 v144, v144, v143
	s_lshl_b32 s56, s12, 11
	s_and_b32 s56, s56, 0x2000
	v_add_u32_e32 v144, s56, v144
	v_lshlrev_b32_e32 v144, 10, v144
	s_lshl_b32 s56, s95, 8
	s_and_b32 s56, s56, 0x300
	v_add_u32_e32 v144, s56, v144
	v_lshl_add_u32 v144, v142, 4, v144
	v_mov_b32_e32 v147, v144
	v_lshlrev_b32_e32 v145, 5, v142
	global_load_dwordx4 v[100:103], v145, s[30:31]
	global_load_dwordx4 v[104:107], v145, s[30:31] offset:16
	global_load_dwordx4 v[228:231], v144, s[44:45]
	v_add_u32_e32 v144, 0x1000, v144
	global_load_dwordx4 v[232:235], v144, s[44:45]
	v_add_u32_e32 v144, 0x1000, v144
	global_load_dwordx4 v[236:239], v144, s[44:45]
	v_add_u32_e32 v144, 0x1000, v144
	global_load_dwordx4 v[240:243], v144, s[44:45]
	v_add_u32_e32 v144, 0x1000, v144
	global_load_dwordx4 v[84:87], v144, s[44:45]
	v_add_u32_e32 v144, 0x1000, v144
	global_load_dwordx4 v[88:91], v144, s[44:45]
	v_add_u32_e32 v144, 0x1000, v144
	global_load_dwordx4 v[92:95], v144, s[44:45]
	v_add_u32_e32 v144, 0x1000, v144
	global_load_dwordx4 v[96:99], v144, s[44:45]
